# kernel entry touches every kernarg cache line at once (later dependent kernarg loads hit the scalar cache)
# speedup vs baseline: 1.0931x; 1.0017x over previous
_Z8fwd_mega6Params:
	s_mov_b32 s98, 1
	s_load_dwordx4 s[4:7], s[0:1], 0x100
	s_load_dword s52, s[0:1], 0x0
	s_load_dword s53, s[0:1], 0x40
	s_load_dword s54, s[0:1], 0x80
	s_load_dword s55, s[0:1], 0xc0
	s_load_dword s56, s[0:1], 0x140
	s_load_dword s57, s[0:1], 0x180
	s_load_dword s58, s[0:1], 0x1c0
	s_load_dword s59, s[0:1], 0x200
	v_and_b32_e32 v137, 0x3ff, v0
	v_writelane_b32 v242, s2, 0
	s_waitcnt lgkmcnt(0)
	v_writelane_b32 v242, s4, 1
	s_nop 1
	v_writelane_b32 v242, s5, 2
	v_writelane_b32 v242, s6, 3
	v_writelane_b32 v242, s7, 4
	v_cmp_eq_u32_e64 s[4:5], 0, v137
	s_mov_b64 s[2:3], exec
	s_nop 0
	v_writelane_b32 v242, s4, 5
	s_nop 1
	v_writelane_b32 v242, s5, 6
	s_and_b64 s[4:5], s[2:3], s[4:5]
	s_mov_b64 exec, s[4:5]
	s_add_i32 s4, 0, 0x12008
	v_mov_b32_e32 v2, 0
	v_mov_b32_e32 v3, v2
	v_mov_b32_e32 v1, s4
	ds_write_b64 v1, v[2:3]
	s_or_b64 exec, exec, s[2:3]
	s_load_dwordx4 s[4:7], s[0:1], 0x100
	s_waitcnt lgkmcnt(0)
	s_barrier
	s_add_u32 s2, s6, 0x30f4100
	s_addc_u32 s3, s7, 0
	v_writelane_b32 v242, s2, 7
	s_nop 1
	v_writelane_b32 v242, s3, 8
	s_getreg_b32 s2, hwreg(HW_REG_XCC_ID, 0, 4)
	s_and_b32 s2, s2, 15
	v_writelane_b32 v242, s2, 9
	s_mov_b64 s[2:3], exec
	v_readlane_b32 s4, v242, 5
	v_readlane_b32 s5, v242, 6
	s_and_b64 s[4:5], s[2:3], s[4:5]
	s_mov_b64 exec, s[4:5]
	s_cbranch_execz .LBB0_5
	s_mov_b64 s[4:5], exec
	v_mbcnt_lo_u32_b32 v1, s4, 0
	v_mbcnt_hi_u32_b32 v1, s5, v1
	v_cmp_eq_u32_e32 vcc, 0, v1
	s_and_b64 s[6:7], exec, vcc
	s_mov_b64 exec, s[6:7]
	s_cbranch_execz .LBB0_5
	v_readlane_b32 s6, v242, 9
	s_bcnt1_i32_b64 s4, s[4:5]
	s_lshl_b32 s6, s6, 8
	v_mov_b32_e32 v2, s4
	v_readlane_b32 s4, v242, 7
	v_mov_b32_e32 v1, s6
	v_readlane_b32 s5, v242, 8
	s_nop 4
	global_atomic_add v1, v2, s[4:5] offset:1024
